# layer 1-3 weight transposes (all but w_mod) deferred to idle workgroups of in-proj round 2 and gate/up last round, hand-written LDS-free transpose
# speedup vs baseline: 1.1432x; 1.0158x over previous
; #define INP(i) ((const float*)ld_ptr(pb, (i)))
; __device__ __forceinline__ void transpose_item(const float* W, int K, int N, bf16_t* WT, int n0, int k0, int drow0, float* scr, int lane) {
;     float wreg[32];
; #pragma unroll
;     for (int i = 0; i < 32; ++i) wreg[i] = W[(size_t)(k0 + 2 * i + (lane >> 5)) * N + n0 + (lane & 31)];
; __global__ void __launch_bounds__(512, 2) hybrid_fwd(Params P) {
;     ...
;         for (int it = gw; it < DEPTH * I_LAYER; it += NGW) {
;             const int l = it / I_LAYER; int r = it % I_LAYER;
;             if (r < I_IN) { const int kb = r / 48, nbk = r % 48; transpose_item(INP(13) + (size_t)l * D * NIN, D, NIN, WIN + (size_t)l * NIN * D, nbk * 32, kb * 64, win_dst_row(nbk * 32), scr, lane); continue; } r -= I_IN;
;             if (r < I_OUT) { const int kb = r / 32, nbk = r % 32; transpose_item(INP(29) + (size_t)l * D * D, D, D, WOUT + (size_t)l * D * D, nbk * 32, kb * 64, nbk * 32, scr, lane); continue; } r -= I_OUT;
;             if (r < I_G) { const int kb = r / 88, nbk = r % 88, n0 = nbk * 32; transpose_item(INP(30) + (size_t)l * D * DFF, D, DFF, WGU + (size_t)l * NGU * D, n0, kb * 64, 256 * (n0 >> 7) + (n0 & 127), scr, lane); continue; } r -= I_G;
;             if (r < I_G) { const int kb = r / 88, nbk = r % 88, n0 = nbk * 32; transpose_item(INP(31) + (size_t)l * D * DFF, D, DFF, WGU + (size_t)l * NGU * D, n0, kb * 64, 256 * (n0 >> 7) + 128 + (n0 & 127), scr, lane); continue; } r -= I_G;
;             if (r < I_DN) { const int kb = r / 32, nbk = r % 32; transpose_item(INP(32) + (size_t)l * DFF * D, DFF, D, WDN + (size_t)l * D * DFF, nbk * 32, kb * 64, nbk * 32, scr, lane); continue; } r -= I_DN;
;             if (r < I_GLU) { const int kb = r / 8, nbk = r % 8; transpose_item(INP(23) + (size_t)l * 65536, 256, 256, WGLU + (size_t)l * 65536, nbk * 32, kb * 64, nbk * 32, scr, lane); continue; } r -= I_GLU;
;             { const int kb = r / 192, nbk = r % 192; transpose_item(INP(11) + (size_t)l * D * 6144, D, 6144, WMOD + (size_t)l * 6144 * D, nbk * 32, kb * 64, nbk * 32, scr, lane); }
.LBB0_76:
	s_mul_hi_i32 s0, s10, 0x79d06a97
	s_lshr_b32 s2, s0, 31
	s_ashr_i32 s0, s0, 12
	s_add_i32 s2, s0, s2
	s_mul_i32 s0, s2, 0xffffde60
	s_add_i32 s8, s10, s0
	s_cmp_lt_i32 s2, 1
	s_cbranch_scc1 .Lp0_keep
	s_cmpk_lt_u32 s8, 0x15a0
	s_cbranch_scc1 .LBB0_75
.Lp0_keep:
	s_cmpk_gt_i32 s8, 0x2ff
	s_mov_b64 s[4:5], -1
	s_cbranch_scc0 .LBB0_98
	s_cmpk_gt_u32 s8, 0x4ff
	s_cbranch_scc0 .LBB0_95
	s_cmpk_gt_u32 s8, 0xa7f
	s_cbranch_scc0 .LBB0_92
	s_cmpk_gt_u32 s8, 0xfff
	s_cbranch_scc0 .LBB0_89
	s_cmpk_gt_u32 s8, 0x157f
	s_cbranch_scc0 .LBB0_86
	s_cmpk_gt_u32 s8, 0x159f
	s_cbranch_scc0 .LBB0_83
	s_add_i32 s0, s8, 0xea60
	ds_read_b64 v[20:21], v15 offset:88
	s_and_b32 s3, s0, 0xffff
	s_mul_i32 s3, s3, 0xaaab
	s_lshr_b32 s3, s3, 23
	s_mul_i32 s4, s3, 0xc0
	s_sub_i32 s0, s0, s4
	s_waitcnt lgkmcnt(0)
	v_readfirstlane_b32 s5, v20
	s_mul_i32 s74, s2, 0x1800000
	v_readfirstlane_b32 s4, v21
	s_mul_hi_i32 s9, s2, 0x1800000
	s_add_u32 s5, s5, s74
	s_addc_u32 s9, s4, s9
	s_mul_i32 s74, s2, 0xc00000
	s_mul_hi_i32 s4, s2, 0xc00000
	s_add_u32 s74, s12, s74
	s_addc_u32 s75, s13, s4
	s_lshl_b32 s0, s0, 5
	s_and_b32 s0, s0, 0xffe0
	s_lshl_b32 s4, s0, 2
	s_add_u32 s4, s5, s4
	v_lshl_add_u32 v3, s3, 6, v4
	s_addc_u32 s5, s9, 0
	v_lshl_add_u64 v[20:21], s[4:5], 0, v[0:1]
	v_add_u32_e32 v24, 2, v3
	v_add_u32_e32 v26, 4, v3
	v_add_u32_e32 v28, 6, v3
	v_add_u32_e32 v30, 8, v3
	v_add_u32_e32 v32, 10, v3
	v_add_u32_e32 v34, 12, v3
	v_add_u32_e32 v36, 14, v3
	v_mad_i64_i32 v[22:23], s[4:5], v3, s31, v[20:21]
	v_mad_i64_i32 v[24:25], s[4:5], v24, s31, v[20:21]
	v_mad_i64_i32 v[26:27], s[4:5], v26, s31, v[20:21]
	v_mad_i64_i32 v[28:29], s[4:5], v28, s31, v[20:21]
	v_mad_i64_i32 v[30:31], s[4:5], v30, s31, v[20:21]
	v_mad_i64_i32 v[32:33], s[4:5], v32, s31, v[20:21]
	v_mad_i64_i32 v[34:35], s[4:5], v34, s31, v[20:21]
	v_mad_i64_i32 v[36:37], s[4:5], v36, s31, v[20:21]
	global_load_dword v38, v[22:23], off
	global_load_dword v39, v[24:25], off
	global_load_dword v40, v[26:27], off
	global_load_dword v41, v[28:29], off
	global_load_dword v42, v[30:31], off
	global_load_dword v43, v[32:33], off
	global_load_dword v44, v[34:35], off
	global_load_dword v45, v[36:37], off
	v_add_u32_e32 v22, 16, v3
	v_add_u32_e32 v24, 18, v3
	v_add_u32_e32 v26, 20, v3
	v_add_u32_e32 v28, 22, v3
	v_add_u32_e32 v30, 24, v3
	v_add_u32_e32 v32, 26, v3
	v_add_u32_e32 v34, 28, v3
	v_add_u32_e32 v36, 30, v3
	v_mad_i64_i32 v[22:23], s[4:5], v22, s31, v[20:21]
	v_mad_i64_i32 v[24:25], s[4:5], v24, s31, v[20:21]
	v_mad_i64_i32 v[26:27], s[4:5], v26, s31, v[20:21]
	v_mad_i64_i32 v[28:29], s[4:5], v28, s31, v[20:21]
	v_mad_i64_i32 v[30:31], s[4:5], v30, s31, v[20:21]
	v_mad_i64_i32 v[32:33], s[4:5], v32, s31, v[20:21]
	v_mad_i64_i32 v[34:35], s[4:5], v34, s31, v[20:21]
	v_mad_i64_i32 v[36:37], s[4:5], v36, s31, v[20:21]
	global_load_dword v46, v[22:23], off
	global_load_dword v47, v[24:25], off
	global_load_dword v48, v[26:27], off
	global_load_dword v49, v[28:29], off
	global_load_dword v50, v[30:31], off
	global_load_dword v51, v[32:33], off
	global_load_dword v52, v[34:35], off
	global_load_dword v53, v[36:37], off
	v_add_u32_e32 v22, 32, v3
	v_add_u32_e32 v24, 34, v3
	v_add_u32_e32 v26, 36, v3
	v_add_u32_e32 v28, 38, v3
	v_add_u32_e32 v30, 40, v3
	v_add_u32_e32 v32, 42, v3
	v_add_u32_e32 v34, 44, v3
	v_add_u32_e32 v36, 46, v3
	v_mad_i64_i32 v[22:23], s[4:5], v22, s31, v[20:21]
	v_mad_i64_i32 v[24:25], s[4:5], v24, s31, v[20:21]
	v_mad_i64_i32 v[26:27], s[4:5], v26, s31, v[20:21]
	v_mad_i64_i32 v[28:29], s[4:5], v28, s31, v[20:21]
	v_mad_i64_i32 v[30:31], s[4:5], v30, s31, v[20:21]
	v_mad_i64_i32 v[32:33], s[4:5], v32, s31, v[20:21]
	v_mad_i64_i32 v[34:35], s[4:5], v34, s31, v[20:21]
	v_mad_i64_i32 v[36:37], s[4:5], v36, s31, v[20:21]
	global_load_dword v54, v[22:23], off
	global_load_dword v55, v[24:25], off
	global_load_dword v56, v[26:27], off
	global_load_dword v57, v[28:29], off
	global_load_dword v58, v[30:31], off
	global_load_dword v59, v[32:33], off
	global_load_dword v60, v[34:35], off
	s_nop 0
	global_load_dword v36, v[36:37], off
	v_add_u32_e32 v22, 48, v3
	v_add_u32_e32 v24, 50, v3
	v_add_u32_e32 v26, 52, v3
	v_add_u32_e32 v28, 54, v3
	v_add_u32_e32 v30, 56, v3
	v_add_u32_e32 v32, 58, v3
	v_add_u32_e32 v34, 60, v3
	v_add_u32_e32 v3, 62, v3
	v_mad_i64_i32 v[22:23], s[4:5], v22, s31, v[20:21]
	v_mad_i64_i32 v[24:25], s[4:5], v24, s31, v[20:21]
	v_mad_i64_i32 v[26:27], s[4:5], v26, s31, v[20:21]
	v_mad_i64_i32 v[28:29], s[4:5], v28, s31, v[20:21]
	v_mad_i64_i32 v[30:31], s[4:5], v30, s31, v[20:21]
	v_mad_i64_i32 v[32:33], s[4:5], v32, s31, v[20:21]
	v_mad_i64_i32 v[34:35], s[4:5], v34, s31, v[20:21]
	v_mad_i64_i32 v[20:21], s[4:5], v3, s31, v[20:21]
	global_load_dword v3, v[22:23], off
	s_nop 0
	global_load_dword v22, v[24:25], off
	global_load_dword v23, v[26:27], off
	s_nop 0
	global_load_dword v24, v[28:29], off
	global_load_dword v25, v[30:31], off
	global_load_dword v26, v[32:33], off
	global_load_dword v27, v[34:35], off
	s_nop 0
	global_load_dword v20, v[20:21], off
	s_waitcnt vmcnt(30)
; __device__ __forceinline__ unsigned cvt_pk_bf16(float lo, float hi) { const f32x2_t v = {lo, hi}; const bf16x2_t b = __builtin_convertvector(v, bf16x2_t); return __builtin_bit_cast(unsigned, b); }
; __device__ __forceinline__ void transpose_item(const float* W, int K, int N, bf16_t* WT, int n0, int k0, int drow0, float* scr, int lane) {
;     ...
; #pragma unroll
;     for (int i = 0; i < 32; ++i) { const int kk = 2 * i + (lane >> 5); scr[kk * 33 + (lane & 31)] = wreg[i]; }
;     asm volatile("s_waitcnt lgkmcnt(0)" ::: "memory");
;     const int c = lane & 7;
; #pragma unroll
;     for (int j = 0; j < 4; ++j) { const int n = (lane >> 3) + 8 * j; const float* s = scr + (8 * c) * 33 + n;
;         u32x4 o; o.x = cvt_pk_bf16(s[0 * 33], s[1 * 33]); o.y = cvt_pk_bf16(s[2 * 33], s[3 * 33]); o.z = cvt_pk_bf16(s[4 * 33], s[5 * 33]); o.w = cvt_pk_bf16(s[6 * 33], s[7 * 33]);
;         *(u32x4*)(WT + (size_t)(drow0 + n) * K + k0 + 8 * c) = o; }
;     asm volatile("s_waitcnt lgkmcnt(0)" ::: "memory");
	ds_write2_b32 v5, v38, v39 offset1:66
	s_waitcnt vmcnt(28)
	ds_write2_b32 v5, v40, v41 offset0:132 offset1:198
	s_waitcnt vmcnt(26)
	ds_write2_b32 v8, v42, v43 offset0:8 offset1:74
	s_waitcnt vmcnt(24)
	ds_write2_b32 v8, v44, v45 offset0:140 offset1:206
	s_waitcnt vmcnt(22)
	ds_write2_b32 v13, v46, v47 offset0:16 offset1:82
	s_waitcnt vmcnt(20)
	ds_write2_b32 v13, v48, v49 offset0:148 offset1:214
	s_waitcnt vmcnt(18)
	ds_write2_b32 v14, v50, v51 offset0:24 offset1:90
	s_waitcnt vmcnt(16)
	ds_write2_b32 v14, v52, v53 offset0:156 offset1:222
	s_waitcnt vmcnt(14)
	ds_write2_b32 v16, v54, v55 offset0:32 offset1:98
	s_waitcnt vmcnt(12)
	ds_write2_b32 v16, v56, v57 offset0:164 offset1:230
	s_waitcnt vmcnt(10)
	ds_write2_b32 v17, v58, v59 offset0:40 offset1:106
	s_waitcnt vmcnt(8)
	ds_write2_b32 v17, v60, v36 offset0:172 offset1:238
	s_waitcnt vmcnt(6)
	ds_write2_b32 v18, v3, v22 offset0:48 offset1:114
	s_waitcnt vmcnt(4)
	ds_write2_b32 v18, v23, v24 offset0:180 offset1:246
	s_waitcnt vmcnt(2)
	ds_write2_b32 v19, v25, v26 offset0:56 offset1:122
	s_waitcnt vmcnt(0)
	ds_write2_b32 v19, v27, v20 offset0:188 offset1:254
	s_waitcnt lgkmcnt(0)
	ds_read2_b32 v[24:25], v7 offset0:33 offset1:41
	ds_read2_b32 v[26:27], v7 offset1:8
	ds_read2_b32 v[28:29], v7 offset0:66 offset1:74
	ds_read2_b32 v[30:31], v7 offset0:99 offset1:107
	ds_read2_b32 v[32:33], v7 offset0:132 offset1:140
	ds_read2_b32 v[34:35], v7 offset0:165 offset1:173
	ds_read2_b32 v[36:37], v7 offset0:198 offset1:206
	ds_read2_b32 v[38:39], v7 offset0:231 offset1:239
	s_lshl_b32 s3, s3, 7
	s_add_u32 s4, s74, s3
	v_add_u32_e32 v42, s0, v6
	s_addc_u32 s5, s75, 0
	v_mov_b32_e32 v3, v1
	v_ashrrev_i32_e32 v43, 31, v42
	v_lshl_add_u64 v[40:41], s[4:5], 0, v[2:3]
	v_lshlrev_b64 v[42:43], 11, v[42:43]
	s_waitcnt lgkmcnt(6)
	v_cvt_pk_bf16_f32 v20, v26, v24
	s_waitcnt lgkmcnt(4)
	v_cvt_pk_bf16_f32 v21, v28, v30
	s_waitcnt lgkmcnt(2)
	v_cvt_pk_bf16_f32 v22, v32, v34
	s_waitcnt lgkmcnt(0)
	v_cvt_pk_bf16_f32 v23, v36, v38
	v_lshl_add_u64 v[42:43], v[40:41], 0, v[42:43]
	v_add_u32_e32 v24, s0, v10
	global_store_dwordx4 v[42:43], v[20:23], off
	s_mov_b64 s[4:5], 0
	s_nop 0
	v_cvt_pk_bf16_f32 v20, v27, v25
	v_ashrrev_i32_e32 v25, 31, v24
	v_cvt_pk_bf16_f32 v21, v29, v31
	v_cvt_pk_bf16_f32 v22, v33, v35
	v_cvt_pk_bf16_f32 v23, v37, v39
	v_lshlrev_b64 v[24:25], 11, v[24:25]
	ds_read2_b32 v[26:27], v7 offset0:49 offset1:57
	ds_read2_b32 v[28:29], v7 offset0:16 offset1:24
	ds_read2_b32 v[30:31], v7 offset0:82 offset1:90
	ds_read2_b32 v[32:33], v7 offset0:115 offset1:123
	ds_read2_b32 v[34:35], v7 offset0:148 offset1:156
	ds_read2_b32 v[36:37], v7 offset0:181 offset1:189
	ds_read2_b32 v[38:39], v7 offset0:214 offset1:222
	ds_read2_b32 v[42:43], v7 offset0:247 offset1:255
	v_lshl_add_u64 v[24:25], v[40:41], 0, v[24:25]
	global_store_dwordx4 v[24:25], v[20:23], off
	v_add_u32_e32 v24, s0, v11
	v_ashrrev_i32_e32 v25, 31, v24
	v_lshlrev_b64 v[24:25], 11, v[24:25]
	s_waitcnt lgkmcnt(6)
	v_cvt_pk_bf16_f32 v20, v28, v26
	s_waitcnt lgkmcnt(4)
	v_cvt_pk_bf16_f32 v21, v30, v32
	s_waitcnt lgkmcnt(2)
	v_cvt_pk_bf16_f32 v22, v34, v36
	s_waitcnt lgkmcnt(0)
	v_cvt_pk_bf16_f32 v23, v38, v42
	v_lshl_add_u64 v[24:25], v[40:41], 0, v[24:25]
	global_store_dwordx4 v[24:25], v[20:23], off
	v_add_u32_e32 v24, s0, v12
	v_ashrrev_i32_e32 v25, 31, v24
	v_lshlrev_b64 v[24:25], 11, v[24:25]
	v_cvt_pk_bf16_f32 v20, v29, v27
	v_cvt_pk_bf16_f32 v21, v31, v33
	v_cvt_pk_bf16_f32 v22, v35, v37
	v_cvt_pk_bf16_f32 v23, v39, v43
	v_lshl_add_u64 v[24:25], v[40:41], 0, v[24:25]
	global_store_dwordx4 v[24:25], v[20:23], off
	s_waitcnt lgkmcnt(0)

; __device__ __forceinline__ int win_dst_row(int c) {
;     if (c < 512) { const int tile = c >> 8, cc = c & 255; return tile * 256 + 128 * ((cc & 63) >> 5) + 32 * (cc >> 6) + (cc & 31); }
;     if (c < 640) { const int cc = c - 512; return 512 + 128 * ((cc & 63) >> 5) + 32 * (cc >> 6) + (cc & 31); }
;     if (c < 768) { const int cc = c - 640; return 512 + 128 * (cc >> 6) + 64 + (cc & 63); }
;     if (c < 1024) return c;
;     if (c < 1280) { const int cc = c - 1024; return 1024 + 256 * (cc >> 7) + (cc & 127); }
;     { const int cc = c - 1280; return 1024 + 256 * (cc >> 7) + 128 + (cc & 127); }
; }
; __global__ void __launch_bounds__(512, 2) hybrid_fwd(Params P) {
;     ...
;         for (int i = gt; i < DEPTH * NSB * 26 * 64; i += NGT) { const int c4 = i & 63, r = (i >> 6) % 26, lb = i / (64 * 26);
;             *(f32x4*)(out + O_CS + ((size_t)lb * 30 + r) * 256 + c4 * 4) = *(const f32x4*)(scp + ((size_t)lb * 30 + r + 4) * 256 + c4 * 4); } }
.Lcpx_c:
	s_min_u32 s7, s0, s1
	s_mul_hi_u32 s23, s7, s27
	s_mul_i32 s18, s23, 26
	s_sub_u32 s7, s7, s18
	s_mul_i32 s23, s23, 0x7800
	s_lshl_b32 s7, s7, 10
	s_add_u32 s7, s7, s23
	v_add_u32_e32 v4, s7, v16
	global_load_dwordx4 v[88:91], v4, s[10:11]
	s_add_u32 s0, s0, 928
	s_min_u32 s7, s0, s1
	s_mul_hi_u32 s23, s7, s27
	s_mul_i32 s18, s23, 26
	s_sub_u32 s7, s7, s18
	s_mul_i32 s23, s23, 0x7800
	s_lshl_b32 s7, s7, 10
	s_add_u32 s7, s7, s23
	v_add_u32_e32 v5, s7, v16
	global_load_dwordx4 v[92:95], v5, s[10:11]
	s_add_u32 s0, s0, 928
	s_min_u32 s7, s0, s1
	s_mul_hi_u32 s23, s7, s27
	s_mul_i32 s18, s23, 26
	s_sub_u32 s7, s7, s18
	s_mul_i32 s23, s23, 0x7800
	s_lshl_b32 s7, s7, 10
	s_add_u32 s7, s7, s23
	v_add_u32_e32 v6, s7, v16
	global_load_dwordx4 v[96:99], v6, s[10:11]
	s_add_u32 s0, s0, 928
	s_min_u32 s7, s0, s1
	s_mul_hi_u32 s23, s7, s27
	s_mul_i32 s18, s23, 26
	s_sub_u32 s7, s7, s18
	s_mul_i32 s23, s23, 0x7800
	s_lshl_b32 s7, s7, 10
	s_add_u32 s7, s7, s23
	v_add_u32_e32 v7, s7, v16
	global_load_dwordx4 v[100:103], v7, s[10:11]
	s_add_u32 s0, s0, 928
	s_waitcnt vmcnt(3)
	global_store_dwordx4 v4, v[88:91], s[20:21]
	s_waitcnt vmcnt(3)
	global_store_dwordx4 v5, v[92:95], s[20:21]
	s_waitcnt vmcnt(3)
	global_store_dwordx4 v6, v[96:99], s[20:21]
	s_waitcnt vmcnt(3)
	global_store_dwordx4 v7, v[100:103], s[20:21]
	s_cmp_le_u32 s0, s1
	s_cbranch_scc1 .Lcpx_c
	s_cmp_lt_u32 s96, 3
	s_cbranch_scc0 .Ltr_a_end
	s_add_i32 s37, s96, 1
	v_mbcnt_lo_u32_b32 v6, -1, 0
	v_mbcnt_hi_u32_b32 v6, -1, v6
	v_lshrrev_b32_e32 v7, 5, v6
	v_and_b32_e32 v6, 31, v6
	s_add_u32 s0, s29, 0
	s_mov_b32 s1, 2688
	s_cmp_lt_u32 s0, s1
	s_cbranch_scc0 .Ltr_a_end
.Ltr_a_item:
	s_cmp_lt_u32 s0, 768
	s_cbranch_scc0 .Ltr_a_k1
	s_sub_u32 s7, s0, 0
	s_mov_b32 s38, 0x20468
	s_mov_b32 s39, 0x600000
	s_mov_b32 s40, 0x2800000
	s_mov_b32 s41, 0x300000
	s_mov_b32 s43, 1536
	s_mov_b32 s44, 1024
	s_mul_hi_u32 s18, s7, 0x5555556
	s_mul_i32 s23, s18, 48
	s_sub_u32 s23, s7, s23
	s_lshl_b32 s45, s23, 5
	s_lshl_b32 s46, s18, 6
	s_cmp_lt_u32 s45, 512
	s_cbranch_scc0 .Ltr_a_w1
	s_and_b32 s47, s45, 0x100
	s_bfe_u32 s18, s45, 0x10005
	s_lshl_b32 s18, s18, 7
	s_add_u32 s47, s47, s18
	s_bfe_u32 s18, s45, 0x20006
	s_lshl_b32 s18, s18, 5
	s_add_u32 s47, s47, s18
	s_branch .Ltr_a_wd
.Ltr_a_w1:
	s_cmp_lt_u32 s45, 640
	s_cbranch_scc0 .Ltr_a_w2
	s_sub_u32 s23, s45, 512
	s_bfe_u32 s18, s23, 0x10005
	s_lshl_b32 s18, s18, 7
	s_add_u32 s47, s18, 512
	s_lshr_b32 s18, s23, 6
	s_lshl_b32 s18, s18, 5
	s_add_u32 s47, s47, s18
	s_branch .Ltr_a_wd
.Ltr_a_w2:
	s_cmp_lt_u32 s45, 768
	s_cbranch_scc0 .Ltr_a_w3
	s_sub_u32 s23, s45, 640
	s_lshr_b32 s18, s23, 6
	s_lshl_b32 s18, s18, 7
	s_add_u32 s47, s18, 576
	s_and_b32 s18, s23, 63
	s_add_u32 s47, s47, s18
	s_branch .Ltr_a_wd
.Ltr_a_w3:
	s_cmp_lt_u32 s45, 1024
	s_cbranch_scc0 .Ltr_a_w4
	s_mov_b32 s47, s45
	s_branch .Ltr_a_wd
.Ltr_a_w4:
	s_cmp_lt_u32 s45, 1280
	s_cbranch_scc0 .Ltr_a_w5
	s_sub_u32 s23, s45, 1024
	s_lshr_b32 s18, s23, 7
	s_lshl_b32 s18, s18, 8
	s_add_u32 s47, s18, 1024
	s_and_b32 s18, s23, 127
	s_add_u32 s47, s47, s18
	s_branch .Ltr_a_wd
.Ltr_a_w5:
	s_sub_u32 s23, s45, 1280
	s_lshr_b32 s18, s23, 7
	s_lshl_b32 s18, s18, 8
	s_add_u32 s47, s18, 1152
	s_and_b32 s18, s23, 127
	s_add_u32 s47, s47, s18

; #define INP(i) ((const float*)ld_ptr(pb, (i)))
; __global__ void __launch_bounds__(512, 2) hybrid_fwd(Params P) {
;     ...
;             if (r < I_IN) { const int kb = r / 48, nbk = r % 48; transpose_item(INP(13) + (size_t)l * D * NIN, D, NIN, WIN + (size_t)l * NIN * D, nbk * 32, kb * 64, win_dst_row(nbk * 32), scr, lane); continue; } r -= I_IN;
;             if (r < I_OUT) { const int kb = r / 32, nbk = r % 32; transpose_item(INP(29) + (size_t)l * D * D, D, D, WOUT + (size_t)l * D * D, nbk * 32, kb * 64, nbk * 32, scr, lane); continue; } r -= I_OUT;
;             if (r < I_G) { const int kb = r / 88, nbk = r % 88, n0 = nbk * 32; transpose_item(INP(30) + (size_t)l * D * DFF, D, DFF, WGU + (size_t)l * NGU * D, n0, kb * 64, 256 * (n0 >> 7) + (n0 & 127), scr, lane); continue; } r -= I_G;
;             if (r < I_G) { const int kb = r / 88, nbk = r % 88, n0 = nbk * 32; transpose_item(INP(31) + (size_t)l * D * DFF, D, DFF, WGU + (size_t)l * NGU * D, n0, kb * 64, 256 * (n0 >> 7) + 128 + (n0 & 127), scr, lane); continue; } r -= I_G;
;             if (r < I_DN) { const int kb = r / 32, nbk = r % 32; transpose_item(INP(32) + (size_t)l * DFF * D, DFF, D, WDN + (size_t)l * D * DFF, nbk * 32, kb * 64, nbk * 32, scr, lane); continue; } r -= I_DN;
;             if (r < I_GLU) { const int kb = r / 8, nbk = r % 8; transpose_item(INP(23) + (size_t)l * 65536, 256, 256, WGLU + (size_t)l * 65536, nbk * 32, kb * 64, nbk * 32, scr, lane); continue; } r -= I_GLU;
.Ltr_a_k1:
	s_cmp_lt_u32 s0, 1280
	s_cbranch_scc0 .Ltr_a_k2
	s_sub_u32 s7, s0, 768
	s_mov_b32 s38, 0x204e8
	s_mov_b32 s39, 0x400000
	s_mov_b32 s40, 0x3400000
	s_mov_b32 s41, 0x200000
	s_mov_b32 s43, 1024
	s_mov_b32 s44, 1024
	s_lshr_b32 s18, s7, 5
	s_and_b32 s23, s7, 31
	s_lshl_b32 s45, s23, 5
	s_lshl_b32 s46, s18, 6
	s_mov_b32 s47, s45
	s_branch .Ltr_a_go
.Ltr_a_k2:
	s_cmp_lt_u32 s0, 2688
	s_cbranch_scc0 .Ltr_a_k3
	s_sub_u32 s7, s0, 1280
	s_mov_b32 s38, 0x204f0
	s_mov_b32 s39, 0xb00000
	s_mov_b32 s40, 0x3c00000
	s_mov_b32 s41, 0xb00000
	s_mov_b32 s43, 2816
	s_mov_b32 s44, 1024
	s_mul_hi_u32 s18, s7, 0x2e8ba2f
	s_mul_i32 s23, s18, 88
	s_sub_u32 s23, s7, s23
	s_lshl_b32 s45, s23, 5
	s_lshl_b32 s46, s18, 6
	s_lshr_b32 s18, s45, 7
	s_lshl_b32 s18, s18, 8
	s_and_b32 s47, s45, 127
	s_add_u32 s47, s47, s18
	s_branch .Ltr_a_go
.Ltr_a_k3:
	s_cmp_lt_u32 s0, 4096
	s_cbranch_scc0 .Ltr_a_k4
	s_sub_u32 s7, s0, 2688
	s_mov_b32 s38, 0x204f8
	s_mov_b32 s39, 0xb00000
	s_mov_b32 s40, 0x3c00000
	s_mov_b32 s41, 0xb00000
	s_mov_b32 s43, 2816
	s_mov_b32 s44, 1024
	s_mul_hi_u32 s18, s7, 0x2e8ba2f
	s_mul_i32 s23, s18, 88
	s_sub_u32 s23, s7, s23
	s_lshl_b32 s45, s23, 5
	s_lshl_b32 s46, s18, 6
	s_lshr_b32 s18, s45, 7
	s_lshl_b32 s18, s18, 8
	s_and_b32 s47, s45, 127
	s_add_u32 s47, s47, s18
	s_add_u32 s47, s47, 128
	s_branch .Ltr_a_go
.Ltr_a_k4:
	s_cmp_lt_u32 s0, 5504
	s_cbranch_scc0 .Ltr_a_k5
	s_sub_u32 s7, s0, 4096
	s_mov_b32 s38, 0x20500
	s_mov_b32 s39, 0xb00000
	s_mov_b32 s40, 0x6800000
	s_mov_b32 s41, 0x580000
	s_mov_b32 s43, 1024
	s_mov_b32 s44, 2816
	s_lshr_b32 s18, s7, 5
	s_and_b32 s23, s7, 31
	s_lshl_b32 s45, s23, 5
	s_lshl_b32 s46, s18, 6
	s_mov_b32 s47, s45
	s_branch .Ltr_a_go
.Ltr_a_k5:
	s_cmp_lt_u32 s0, 5536
	s_cbranch_scc0 .Ltr_a_next
	s_sub_u32 s7, s0, 5504
	s_mov_b32 s38, 0x204b8
	s_mov_b32 s39, 0x40000
	s_mov_b32 s40, 0x1600000
	s_mov_b32 s41, 0x20000
	s_mov_b32 s43, 256
	s_mov_b32 s44, 256
	s_lshr_b32 s18, s7, 3
	s_and_b32 s23, s7, 7
	s_lshl_b32 s45, s23, 5
	s_lshl_b32 s46, s18, 6
	s_mov_b32 s47, s45
	s_branch .Ltr_a_go
; __device__ __forceinline__ unsigned cvt_pk_bf16(float lo, float hi) { const f32x2_t v = {lo, hi}; const bf16x2_t b = __builtin_convertvector(v, bf16x2_t); return __builtin_bit_cast(unsigned, b); }
; __device__ __forceinline__ void transpose_item(const float* W, int K, int N, bf16_t* WT, int n0, int k0, int drow0, float* scr, int lane) {
;     float wreg[32];
; #pragma unroll
;     for (int i = 0; i < 32; ++i) wreg[i] = W[(size_t)(k0 + 2 * i + (lane >> 5)) * N + n0 + (lane & 31)];
; #pragma unroll
;     for (int i = 0; i < 32; ++i) { const int kk = 2 * i + (lane >> 5); scr[kk * 33 + (lane & 31)] = wreg[i]; }
;     asm volatile("s_waitcnt lgkmcnt(0)" ::: "memory");
;     const int c = lane & 7;
; #pragma unroll
;     for (int j = 0; j < 4; ++j) { const int n = (lane >> 3) + 8 * j; const float* s = scr + (8 * c) * 33 + n;
;         u32x4 o; o.x = cvt_pk_bf16(s[0 * 33], s[1 * 33]); o.y = cvt_pk_bf16(s[2 * 33], s[3 * 33]); o.z = cvt_pk_bf16(s[4 * 33], s[5 * 33]); o.w = cvt_pk_bf16(s[6 * 33], s[7 * 33]);
;         *(u32x4*)(WT + (size_t)(drow0 + n) * K + k0 + 8 * c) = o; }
.Ltr_a_go:
	v_mov_b32_e32 v0, s38
	ds_read_b64 v[0:1], v0
	v_mov_b32_e32 v8, 0x20518
	ds_read_b64 v[8:9], v8
	s_mul_i32 s39, s39, s37
	s_mul_i32 s41, s41, s37
	s_add_u32 s40, s40, s41
	s_mul_i32 s7, s46, s43
	s_add_u32 s7, s7, s45
	s_lshl_b32 s7, s7, 2
	s_add_u32 s39, s39, s7
	s_mul_i32 s7, s47, s44
	s_add_u32 s7, s7, s46
	s_lshl_b32 s7, s7, 1
	s_add_u32 s40, s40, s7
	v_mad_u32_u24 v4, v7, s43, v6
	v_lshlrev_b32_e32 v4, 2, v4
	v_mul_u32_u24_e32 v5, s44, v6
	v_lshlrev_b32_e32 v5, 1, v5
	v_lshl_add_u32 v5, v7, 4, v5
	s_lshl_b32 s18, s43, 3
	s_waitcnt lgkmcnt(0)
	v_readfirstlane_b32 s10, v0
	v_readfirstlane_b32 s11, v1
	v_readfirstlane_b32 s20, v8
	v_readfirstlane_b32 s21, v9
	s_nop 0
	s_add_u32 s10, s10, s39
	s_addc_u32 s11, s11, 0
	s_add_u32 s20, s20, s40
	s_addc_u32 s21, s21, 0
	global_load_dword v32, v4, s[10:11]
	s_add_u32 s10, s10, s18
	s_addc_u32 s11, s11, 0
	global_load_dword v33, v4, s[10:11]
	s_add_u32 s10, s10, s18
	s_addc_u32 s11, s11, 0
	global_load_dword v34, v4, s[10:11]
	s_add_u32 s10, s10, s18
	s_addc_u32 s11, s11, 0
	global_load_dword v35, v4, s[10:11]
	s_add_u32 s10, s10, s18
	s_addc_u32 s11, s11, 0
	global_load_dword v36, v4, s[10:11]
	s_add_u32 s10, s10, s18
	s_addc_u32 s11, s11, 0
	global_load_dword v37, v4, s[10:11]
	s_add_u32 s10, s10, s18
	s_addc_u32 s11, s11, 0
	global_load_dword v38, v4, s[10:11]
	s_add_u32 s10, s10, s18
	s_addc_u32 s11, s11, 0
	global_load_dword v39, v4, s[10:11]
	s_add_u32 s10, s10, s18
	s_addc_u32 s11, s11, 0
	global_load_dword v40, v4, s[10:11]
	s_add_u32 s10, s10, s18
	s_addc_u32 s11, s11, 0
	global_load_dword v41, v4, s[10:11]
	s_add_u32 s10, s10, s18
	s_addc_u32 s11, s11, 0
	global_load_dword v42, v4, s[10:11]
	s_add_u32 s10, s10, s18
	s_addc_u32 s11, s11, 0
	global_load_dword v43, v4, s[10:11]
	s_add_u32 s10, s10, s18
	s_addc_u32 s11, s11, 0
	global_load_dword v44, v4, s[10:11]
	s_add_u32 s10, s10, s18
	s_addc_u32 s11, s11, 0
	global_load_dword v45, v4, s[10:11]
	s_add_u32 s10, s10, s18
	s_addc_u32 s11, s11, 0
	global_load_dword v46, v4, s[10:11]
	s_add_u32 s10, s10, s18
	s_addc_u32 s11, s11, 0
	global_load_dword v47, v4, s[10:11]
	s_add_u32 s10, s10, s18
	s_addc_u32 s11, s11, 0
	global_load_dword v48, v4, s[10:11]
	s_add_u32 s10, s10, s18
	s_addc_u32 s11, s11, 0
	global_load_dword v49, v4, s[10:11]
	s_add_u32 s10, s10, s18
	s_addc_u32 s11, s11, 0
	global_load_dword v50, v4, s[10:11]
	s_add_u32 s10, s10, s18
	s_addc_u32 s11, s11, 0
	global_load_dword v51, v4, s[10:11]
	s_add_u32 s10, s10, s18
	s_addc_u32 s11, s11, 0
	global_load_dword v52, v4, s[10:11]
	s_add_u32 s10, s10, s18
	s_addc_u32 s11, s11, 0
	global_load_dword v53, v4, s[10:11]
	s_add_u32 s10, s10, s18
	s_addc_u32 s11, s11, 0
	global_load_dword v54, v4, s[10:11]
	s_add_u32 s10, s10, s18
	s_addc_u32 s11, s11, 0
	global_load_dword v55, v4, s[10:11]
	s_add_u32 s10, s10, s18
	s_addc_u32 s11, s11, 0
	global_load_dword v56, v4, s[10:11]
	s_add_u32 s10, s10, s18
	s_addc_u32 s11, s11, 0
	global_load_dword v57, v4, s[10:11]
	s_add_u32 s10, s10, s18
	s_addc_u32 s11, s11, 0
	global_load_dword v58, v4, s[10:11]
	s_add_u32 s10, s10, s18
	s_addc_u32 s11, s11, 0
	global_load_dword v59, v4, s[10:11]
	s_add_u32 s10, s10, s18
	s_addc_u32 s11, s11, 0
	global_load_dword v60, v4, s[10:11]
	s_add_u32 s10, s10, s18
	s_addc_u32 s11, s11, 0
	global_load_dword v61, v4, s[10:11]
	s_add_u32 s10, s10, s18
	s_addc_u32 s11, s11, 0
	global_load_dword v62, v4, s[10:11]
	s_add_u32 s10, s10, s18
	s_addc_u32 s11, s11, 0
	global_load_dword v63, v4, s[10:11]
	s_waitcnt vmcnt(0)
	v_permlane32_swap_b32 v32, v36
	v_permlane32_swap_b32 v33, v37
	v_permlane32_swap_b32 v34, v38
	v_permlane32_swap_b32 v35, v39
	s_nop 1
	v_cvt_pk_bf16_f32 v32, v32, v36
	v_cvt_pk_bf16_f32 v33, v33, v37
	v_cvt_pk_bf16_f32 v34, v34, v38
	v_cvt_pk_bf16_f32 v35, v35, v39
	global_store_dwordx4 v5, v[32:35], s[20:21]
	v_permlane32_swap_b32 v40, v44
	v_permlane32_swap_b32 v41, v45
	v_permlane32_swap_b32 v42, v46
	v_permlane32_swap_b32 v43, v47
	s_nop 1
	v_cvt_pk_bf16_f32 v40, v40, v44
	v_cvt_pk_bf16_f32 v41, v41, v45
	v_cvt_pk_bf16_f32 v42, v42, v46
	v_cvt_pk_bf16_f32 v43, v43, v47
	global_store_dwordx4 v5, v[40:43], s[20:21] offset:32
	v_permlane32_swap_b32 v48, v52
	v_permlane32_swap_b32 v49, v53
	v_permlane32_swap_b32 v50, v54
	v_permlane32_swap_b32 v51, v55
	s_nop 1
	v_cvt_pk_bf16_f32 v48, v48, v52
	v_cvt_pk_bf16_f32 v49, v49, v53
	v_cvt_pk_bf16_f32 v50, v50, v54
	v_cvt_pk_bf16_f32 v51, v51, v55
	global_store_dwordx4 v5, v[48:51], s[20:21] offset:64
	v_permlane32_swap_b32 v56, v60
	v_permlane32_swap_b32 v57, v61
	v_permlane32_swap_b32 v58, v62
	v_permlane32_swap_b32 v59, v63
	s_nop 1
	v_cvt_pk_bf16_f32 v56, v56, v60
	v_cvt_pk_bf16_f32 v57, v57, v61
	v_cvt_pk_bf16_f32 v58, v58, v62
	v_cvt_pk_bf16_f32 v59, v59, v63
	global_store_dwordx4 v5, v[56:59], s[20:21] offset:96
.Ltr_a_next:
	s_add_u32 s0, s0, 928
	s_cmp_lt_u32 s0, s1
	s_cbranch_scc1 .Ltr_a_item
.Ltr_a_end:
.Lcpx_skip:
	s_waitcnt vmcnt(0) lgkmcnt(0)
	s_lshl_b32 s0, s51, 6
	v_sub_u32_e32 v0, 0, v188
	v_cmp_eq_u32_e32 vcc, s0, v0
	s_waitcnt vmcnt(0)
	s_barrier
	s_and_saveexec_b64 s[0:1], vcc
	s_cbranch_execz .LBB0_909
	v_readlane_b32 s3, v253, 8
	s_getreg_b32 s2, hwreg(HW_REG_XCC_ID, 0, 4)
	s_and_b32 s18, s2, 15
	v_mov_b32_e32 v0, s3
	ds_read_b32 v2, v0
	v_readlane_b32 s3, v253, 9
	s_waitcnt lgkmcnt(0)
	v_cmp_ne_u32_e32 vcc, 0, v2
	v_mov_b32_e32 v0, s3
	ds_read_b32 v0, v0
	s_cbranch_vccnz .LBB0_873
	s_add_u32 s2, s8, 0x1000
	s_addc_u32 s3, s9, 0
	s_add_u32 s4, s8, 0x1100
	s_addc_u32 s5, s9, 0
	s_add_u32 s6, s8, 0x1200
	s_addc_u32 s7, s9, 0
	s_add_u32 s10, s8, 0x1300
	s_addc_u32 s11, s9, 0
	s_mov_b32 s19, 1
	s_branch .LBB0_861

; #define INP(i) ((const float*)ld_ptr(pb, (i)))
; __global__ void __launch_bounds__(512, 2) hybrid_fwd(Params P) {
;     ...
;         for (int it = gw; it < DEPTH * I_LAYER; it += NGW) {
;             const int l = it / I_LAYER; int r = it % I_LAYER;
;             if (r < I_IN) { const int kb = r / 48, nbk = r % 48; transpose_item(INP(13) + (size_t)l * D * NIN, D, NIN, WIN + (size_t)l * NIN * D, nbk * 32, kb * 64, win_dst_row(nbk * 32), scr, lane); continue; } r -= I_IN;
.LBB0_1796:
	v_readlane_b32 s29, v253, 0
	v_readlane_b32 s30, v253, 2
	s_nop 3
	s_cmp_lt_u32 s29, 172
	s_cbranch_scc1 .Ltr_b_end
	s_sub_u32 s29, s29, 172
	s_lshl_b32 s29, s29, 3
	s_add_u32 s29, s29, s30
	s_cmp_lt_u32 s96, 3
	s_cbranch_scc0 .Ltr_b_end
	s_add_i32 s37, s96, 1
	v_mbcnt_lo_u32_b32 v6, -1, 0
	v_mbcnt_hi_u32_b32 v6, -1, v6
	v_lshrrev_b32_e32 v7, 5, v6
	v_and_b32_e32 v6, 31, v6
	s_add_u32 s0, s29, 2688
	s_mov_b32 s1, 5536
	s_cmp_lt_u32 s0, s1
	s_cbranch_scc0 .Ltr_b_end

; __global__ void __launch_bounds__(512, 2) hybrid_fwd(Params P) {
;     ...
;         for (int it = gw; it < DEPTH * I_LAYER; it += NGW) {
.Ltr_b_next:
	s_add_u32 s0, s0, 672
	s_cmp_lt_u32 s0, s1
	s_cbranch_scc1 .Ltr_b_item
